# v66 + helper's v-vector load issued only by the lanes that use it (exec masked to quad<8)
# speedup vs baseline: 1.0010x; 1.0010x over previous
.LBB0_730:
	v_ashrrev_i32_e32 v107, 31, v106
	v_lshlrev_b64 v[98:99], 11, v[106:107]
	v_lshl_add_u64 v[98:99], v[98:99], 0, v[120:121]
	v_lshlrev_b64 v[100:101], 1, v[98:99]
	v_lshl_add_u64 v[102:103], s[12:13], 0, v[100:101]
	v_lshl_add_u64 v[104:105], s[18:19], 0, v[100:101]
	v_lshl_add_u64 v[100:101], s[94:95], 0, v[100:101]
	v_lshlrev_b64 v[98:99], 2, v[98:99]
	v_lshlrev_b64 v[106:107], 12, v[106:107]
	global_load_dwordx2 v[160:161], v[102:103], off
	global_load_dwordx2 v[162:163], v[104:105], off
	global_load_dwordx2 v[158:159], v[100:101], off
	v_lshl_add_u64 v[100:101], s[28:29], 0, v[98:99]
	v_lshl_add_u64 v[98:99], s[30:31], 0, v[98:99]
	v_lshl_add_u64 v[106:107], v[130:131], 0, v[106:107]
	global_load_dword v102, v[100:101], off
	s_and_saveexec_b64 s[66:67], s[6:7]
	global_load_dwordx2 v[156:157], v[106:107], off
	s_or_b64 exec, exec, s[66:67]
	s_waitcnt vmcnt(18)
	v_pk_add_f32 v[110:111], v[12:13], -1.0 op_sel_hi:[1,0]
	global_load_dwordx4 v[98:101], v[98:99], off
	v_pk_add_f32 v[112:113], v[10:11], -1.0 op_sel_hi:[1,0]
	v_lshlrev_b32_e32 v188, 16, v142
	v_and_b32_e32 v189, 0xffff0000, v142
	v_lshlrev_b32_e32 v190, 16, v143
	v_and_b32_e32 v191, 0xffff0000, v143
	v_lshlrev_b32_e32 v106, 16, v140
	v_and_b32_e32 v107, 0xffff0000, v140
	v_lshlrev_b32_e32 v108, 16, v141
	v_and_b32_e32 v109, 0xffff0000, v141
	v_pk_fma_f32 v[110:111], v[8:9], v[110:111], 1.0 op_sel_hi:[1,1,0]
	v_pk_fma_f32 v[112:113], v[6:7], v[112:113], 1.0 op_sel_hi:[1,1,0]
	v_pk_mul_f32 v[108:109], v[110:111], v[108:109]
	v_pk_mul_f32 v[106:107], v[112:113], v[106:107]
	v_lshlrev_b32_e32 v110, 16, v134
	v_and_b32_e32 v111, 0xffff0000, v134
	v_lshlrev_b32_e32 v112, 16, v135
	v_and_b32_e32 v113, 0xffff0000, v135
	v_xor_b32_e32 v143, 0x80000000, v191
	v_xor_b32_e32 v142, 0x80000000, v190
	v_xor_b32_e32 v141, 0x80000000, v189
	v_xor_b32_e32 v140, 0x80000000, v188
	v_pk_mul_f32 v[12:13], v[12:13], v[190:191]
	v_pk_mul_f32 v[10:11], v[10:11], v[188:189]
	ds_write_b128 v124, v[140:143] offset:20480
	ds_write_b128 v124, v[10:13] offset:20992
	ds_write_b128 v124, v[106:109] offset:21248
	ds_write_b128 v124, v[110:113] offset:21504
	s_and_saveexec_b64 s[40:41], s[6:7]
	s_cbranch_execz .LBB0_732
	s_waitcnt vmcnt(18)
	v_lshlrev_b32_e32 v10, 16, v136
	v_and_b32_e32 v11, 0xffff0000, v136
	v_lshlrev_b32_e32 v12, 16, v137
	v_and_b32_e32 v13, 0xffff0000, v137
	ds_write_b128 v186, v[10:13] offset:43008

.LBB0_756:
	v_ashrrev_i32_e32 v107, 31, v106
	v_lshlrev_b64 v[10:11], 11, v[106:107]
	v_lshl_add_u64 v[10:11], v[10:11], 0, v[120:121]
	v_lshlrev_b64 v[12:13], 1, v[10:11]
	v_lshl_add_u64 v[14:15], s[12:13], 0, v[12:13]
	v_lshl_add_u64 v[16:17], s[18:19], 0, v[12:13]
	v_lshl_add_u64 v[12:13], s[94:95], 0, v[12:13]
	v_lshlrev_b64 v[10:11], 2, v[10:11]
	v_lshlrev_b64 v[106:107], 12, v[106:107]
	global_load_dwordx2 v[140:141], v[14:15], off
	global_load_dwordx2 v[142:143], v[16:17], off
	global_load_dwordx2 v[134:135], v[12:13], off
	v_lshl_add_u64 v[12:13], s[28:29], 0, v[10:11]
	v_lshl_add_u64 v[10:11], s[30:31], 0, v[10:11]
	v_lshl_add_u64 v[106:107], v[130:131], 0, v[106:107]
	global_load_dword v14, v[12:13], off
	s_and_saveexec_b64 s[66:67], s[6:7]
	global_load_dwordx2 v[136:137], v[106:107], off
	s_or_b64 exec, exec, s[66:67]
	s_waitcnt vmcnt(19)
	v_pk_add_f32 v[110:111], v[20:21], -1.0 op_sel_hi:[1,0]
	global_load_dwordx4 v[10:13], v[10:11], off
	v_pk_add_f32 v[112:113], v[18:19], -1.0 op_sel_hi:[1,0]
	v_lshlrev_b32_e32 v188, 16, v146
	v_and_b32_e32 v189, 0xffff0000, v146
	v_lshlrev_b32_e32 v190, 16, v147
	v_and_b32_e32 v191, 0xffff0000, v147
	v_lshlrev_b32_e32 v106, 16, v144
	v_and_b32_e32 v107, 0xffff0000, v144
	v_lshlrev_b32_e32 v108, 16, v145
	v_and_b32_e32 v109, 0xffff0000, v145
	v_pk_fma_f32 v[110:111], v[8:9], v[110:111], 1.0 op_sel_hi:[1,1,0]
	v_pk_fma_f32 v[112:113], v[6:7], v[112:113], 1.0 op_sel_hi:[1,1,0]
	v_pk_mul_f32 v[108:109], v[110:111], v[108:109]
	v_pk_mul_f32 v[106:107], v[112:113], v[106:107]
	v_lshlrev_b32_e32 v110, 16, v138
	v_and_b32_e32 v111, 0xffff0000, v138
	v_lshlrev_b32_e32 v112, 16, v139
	v_and_b32_e32 v113, 0xffff0000, v139
	v_xor_b32_e32 v147, 0x80000000, v191
	v_xor_b32_e32 v146, 0x80000000, v190
	v_xor_b32_e32 v145, 0x80000000, v189
	v_xor_b32_e32 v144, 0x80000000, v188
	v_pk_mul_f32 v[20:21], v[20:21], v[190:191]
	v_pk_mul_f32 v[18:19], v[18:19], v[188:189]
	ds_write_b128 v124, v[144:147]
	ds_write_b128 v124, v[18:21] offset:512
	ds_write_b128 v124, v[106:109] offset:768
	ds_write_b128 v124, v[110:113] offset:1024
	s_and_saveexec_b64 s[40:41], s[6:7]
	v_lshlrev_b32_e32 v18, 16, v132
	v_and_b32_e32 v19, 0xffff0000, v132
	v_lshlrev_b32_e32 v20, 16, v133
	v_and_b32_e32 v21, 0xffff0000, v133
	ds_write_b128 v186, v[18:21] offset:40960
	s_or_b64 exec, exec, s[40:41]
	v_pk_mul_f32 v[18:19], v[108:109], v[112:113]
	v_pk_mul_f32 v[20:21], v[106:107], v[110:111]
	v_mul_f32_e32 v19, v5, v19
	v_mul_f32_e32 v21, v3, v21
	v_fmac_f32_e32 v21, v2, v20
	v_fmac_f32_e32 v19, v4, v18
	v_add_f32_e32 v18, v21, v19
	v_mov_b32_e32 v20, 0
	s_nop 0
	v_add_f32_dpp v18, v18, v18 row_ror:8 row_mask:0xf bank_mask:0xf bound_ctrl:1
	s_nop 1
	v_add_f32_dpp v18, v18, v18 row_ror:4 row_mask:0xf bank_mask:0xf bound_ctrl:1
	s_nop 1
	v_add_f32_dpp v19, v18, v18 row_ror:2 row_mask:0xf bank_mask:0xf bound_ctrl:1
	s_nop 1
	v_mov_b32_dpp v20, v19 row_ror:1 row_mask:0xf bank_mask:0xf
	s_and_saveexec_b64 s[40:41], s[8:9]
	s_cbranch_execz .LBB0_764
	s_and_b64 vcc, exec, s[4:5]
	s_mov_b64 s[52:53], -1
	s_cbranch_vccnz .LBB0_761
	v_lshl_add_u32 v18, s46, 4, v167
	v_sub_u32_e32 v18, 0x1fdf, v18
	s_mov_b64 s[52:53], 0

.LBB0_782:
	v_ashrrev_i32_e32 v107, 31, v106
	v_lshlrev_b64 v[18:19], 11, v[106:107]
	v_lshl_add_u64 v[18:19], v[18:19], 0, v[120:121]
	v_lshlrev_b64 v[20:21], 1, v[18:19]
	v_lshl_add_u64 v[22:23], s[12:13], 0, v[20:21]
	v_lshl_add_u64 v[24:25], s[18:19], 0, v[20:21]
	v_lshl_add_u64 v[20:21], s[94:95], 0, v[20:21]
	v_lshlrev_b64 v[18:19], 2, v[18:19]
	v_lshlrev_b64 v[106:107], 12, v[106:107]
	global_load_dwordx2 v[144:145], v[22:23], off
	global_load_dwordx2 v[146:147], v[24:25], off
	global_load_dwordx2 v[138:139], v[20:21], off
	v_lshl_add_u64 v[20:21], s[28:29], 0, v[18:19]
	v_lshl_add_u64 v[18:19], s[30:31], 0, v[18:19]
	v_lshl_add_u64 v[106:107], v[130:131], 0, v[106:107]
	global_load_dword v22, v[20:21], off
	s_and_saveexec_b64 s[66:67], s[6:7]
	global_load_dwordx2 v[132:133], v[106:107], off
	s_or_b64 exec, exec, s[66:67]
	s_waitcnt vmcnt(22)
	v_pk_add_f32 v[110:111], v[92:93], -1.0 op_sel_hi:[1,0]
	global_load_dwordx4 v[18:21], v[18:19], off
	v_pk_add_f32 v[112:113], v[90:91], -1.0 op_sel_hi:[1,0]
	v_lshlrev_b32_e32 v190, 16, v154
	v_and_b32_e32 v191, 0xffff0000, v154
	v_lshlrev_b32_e32 v154, 16, v155
	v_and_b32_e32 v155, 0xffff0000, v155
	v_lshlrev_b32_e32 v106, 16, v152
	v_and_b32_e32 v107, 0xffff0000, v152
	v_lshlrev_b32_e32 v108, 16, v153
	v_and_b32_e32 v109, 0xffff0000, v153
	v_pk_fma_f32 v[110:111], v[8:9], v[110:111], 1.0 op_sel_hi:[1,1,0]
	v_pk_fma_f32 v[112:113], v[6:7], v[112:113], 1.0 op_sel_hi:[1,1,0]
	v_pk_mul_f32 v[108:109], v[110:111], v[108:109]
	v_pk_mul_f32 v[106:107], v[112:113], v[106:107]
	v_lshlrev_b32_e32 v110, 16, v150
	v_and_b32_e32 v111, 0xffff0000, v150
	v_lshlrev_b32_e32 v112, 16, v151
	v_and_b32_e32 v113, 0xffff0000, v151
	v_xor_b32_e32 v153, 0x80000000, v155
	v_xor_b32_e32 v152, 0x80000000, v154
	v_xor_b32_e32 v151, 0x80000000, v191
	v_xor_b32_e32 v150, 0x80000000, v190
	v_pk_mul_f32 v[92:93], v[92:93], v[154:155]
	v_pk_mul_f32 v[90:91], v[90:91], v[190:191]
	ds_write_b128 v124, v[150:153] offset:20480
	ds_write_b128 v124, v[90:93] offset:20992
	ds_write_b128 v124, v[106:109] offset:21248
	ds_write_b128 v124, v[110:113] offset:21504
	s_and_saveexec_b64 s[52:53], s[6:7]
	s_cbranch_execz .LBB0_784
	s_waitcnt vmcnt(22)
	v_lshlrev_b32_e32 v90, 16, v148
	v_and_b32_e32 v91, 0xffff0000, v148
	v_lshlrev_b32_e32 v92, 16, v149
	v_and_b32_e32 v93, 0xffff0000, v149
	ds_write_b128 v186, v[90:93] offset:43008

.LBB0_809:
	v_ashrrev_i32_e32 v107, 31, v106
	v_lshlrev_b64 v[90:91], 11, v[106:107]
	v_lshl_add_u64 v[90:91], v[90:91], 0, v[120:121]
	v_lshlrev_b64 v[92:93], 1, v[90:91]
	v_lshl_add_u64 v[94:95], s[12:13], 0, v[92:93]
	v_lshl_add_u64 v[96:97], s[18:19], 0, v[92:93]
	v_lshl_add_u64 v[92:93], s[94:95], 0, v[92:93]
	v_lshlrev_b64 v[90:91], 2, v[90:91]
	v_lshlrev_b64 v[106:107], 12, v[106:107]
	global_load_dwordx2 v[152:153], v[94:95], off
	global_load_dwordx2 v[154:155], v[96:97], off
	global_load_dwordx2 v[150:151], v[92:93], off
	v_lshl_add_u64 v[92:93], s[28:29], 0, v[90:91]
	v_lshl_add_u64 v[90:91], s[30:31], 0, v[90:91]
	v_lshl_add_u64 v[106:107], v[130:131], 0, v[106:107]
	global_load_dword v94, v[92:93], off
	s_and_saveexec_b64 s[66:67], s[6:7]
	global_load_dwordx2 v[148:149], v[106:107], off
	s_or_b64 exec, exec, s[66:67]
	s_waitcnt vmcnt(23)
	v_pk_add_f32 v[110:111], v[100:101], -1.0 op_sel_hi:[1,0]
	global_load_dwordx4 v[90:93], v[90:91], off
	v_pk_add_f32 v[112:113], v[98:99], -1.0 op_sel_hi:[1,0]
	v_lshlrev_b32_e32 v190, 16, v162
	v_and_b32_e32 v191, 0xffff0000, v162
	v_lshlrev_b32_e32 v162, 16, v163
	v_and_b32_e32 v163, 0xffff0000, v163
	v_lshlrev_b32_e32 v106, 16, v160
	v_and_b32_e32 v107, 0xffff0000, v160
	v_lshlrev_b32_e32 v108, 16, v161
	v_and_b32_e32 v109, 0xffff0000, v161
	v_pk_fma_f32 v[110:111], v[8:9], v[110:111], 1.0 op_sel_hi:[1,1,0]
	v_pk_fma_f32 v[112:113], v[6:7], v[112:113], 1.0 op_sel_hi:[1,1,0]
	v_pk_mul_f32 v[108:109], v[110:111], v[108:109]
	v_pk_mul_f32 v[106:107], v[112:113], v[106:107]
	v_lshlrev_b32_e32 v110, 16, v158
	v_and_b32_e32 v111, 0xffff0000, v158
	v_lshlrev_b32_e32 v112, 16, v159
	v_and_b32_e32 v113, 0xffff0000, v159
	v_xor_b32_e32 v161, 0x80000000, v163
	v_xor_b32_e32 v160, 0x80000000, v162
	v_xor_b32_e32 v159, 0x80000000, v191
	v_xor_b32_e32 v158, 0x80000000, v190
	v_pk_mul_f32 v[100:101], v[100:101], v[162:163]
	v_pk_mul_f32 v[98:99], v[98:99], v[190:191]
	ds_write_b128 v124, v[158:161]
	ds_write_b128 v124, v[98:101] offset:512
	ds_write_b128 v124, v[106:109] offset:768
	ds_write_b128 v124, v[110:113] offset:1024
	s_and_saveexec_b64 s[42:43], s[6:7]
	v_lshlrev_b32_e32 v98, 16, v156
	v_and_b32_e32 v99, 0xffff0000, v156
	v_lshlrev_b32_e32 v100, 16, v157
	v_and_b32_e32 v101, 0xffff0000, v157
	ds_write_b128 v186, v[98:101] offset:40960
	s_or_b64 exec, exec, s[42:43]
	v_pk_mul_f32 v[98:99], v[108:109], v[112:113]
	v_pk_mul_f32 v[100:101], v[106:107], v[110:111]
	v_mul_f32_e32 v99, v5, v99
	v_mul_f32_e32 v101, v3, v101
	v_fmac_f32_e32 v101, v2, v100
	v_fmac_f32_e32 v99, v4, v98
	v_add_f32_e32 v98, v101, v99
	v_mov_b32_e32 v100, 0
	s_nop 0
	v_add_f32_dpp v98, v98, v98 row_ror:8 row_mask:0xf bank_mask:0xf bound_ctrl:1
	s_nop 1
	v_add_f32_dpp v98, v98, v98 row_ror:4 row_mask:0xf bank_mask:0xf bound_ctrl:1
	s_nop 1
	v_add_f32_dpp v99, v98, v98 row_ror:2 row_mask:0xf bank_mask:0xf bound_ctrl:1
	s_nop 1
	v_mov_b32_dpp v100, v99 row_ror:1 row_mask:0xf bank_mask:0xf
	s_and_saveexec_b64 s[42:43], s[8:9]
	s_cbranch_execz .LBB0_817
	s_and_b64 vcc, exec, s[4:5]
	s_mov_b64 s[52:53], -1
	s_cbranch_vccnz .LBB0_814
	v_lshl_add_u32 v98, s47, 4, v167
	v_sub_u32_e32 v98, 0x1fbf, v98
	s_mov_b64 s[52:53], 0
